# HGRN o_inter operand from aq product times exp2(rr) table in LDS (one exp per thread per chunk) instead of 32 exps per wave per chunk; f32 math as before
# speedup vs baseline: 1.0077x; 1.0013x over previous
; #define LAS __attribute__((address_space(3)))
; DI void hgrn_scan_phase(int wv, const P& p_, LAS unsigned char* lds, float* sumsq) {
;     ...
;   for (int it = blockIdx.x; it < 256; it += gridDim.x) {
;     const int b = it >> 5, hh = (it >> 2) & 7, vq = it & 3;
;     __syncthreads();
;     for (int i = tid; i < 32 * 136 / 2; i += 512) ((LAS unsigned*)ST)[i] = 0u;
;     f32x4 sreg[2]; sreg[0] = (f32x4){0.f, 0.f, 0.f, 0.f}; sreg[1] = sreg[0];
;     u32x4 pq[2], pkk[2], plf[2], pv;
;     const size_t gb = (size_t)(b * SEQ) * 1024 + hh * 128;
.LBB0_430:
	s_mov_b64 s[22:23], 0
	v_readlane_b32 s0, v253, 16
	s_waitcnt vmcnt(4)
	v_mbcnt_lo_u32_b32 v0, -1, 0
	v_mbcnt_hi_u32_b32 v0, -1, v0
	v_readlane_b32 s1, v253, 17
	s_add_i32 s66, s33, -1
	v_add_u32_e32 v0, s69, v0
	s_andn2_b64 vcc, exec, s[0:1]
	s_cbranch_vccnz .LBB0_429
; #define LAS __attribute__((address_space(3)))
; DI unsigned pk2(float a, float b) { typedef __bf16 bf2 __attribute__((ext_vector_type(2))); bf2 v; v[0] = (__bf16)a; v[1] = (__bf16)b; return __builtin_bit_cast(unsigned, v); }
; DI float bf2f(bf16_t v) { return __uint_as_float(((unsigned)v) << 16); }
; DI void lds_barrier() { asm volatile("s_waitcnt lgkmcnt(0)\n\ts_barrier" ::: "memory"); }
; DI void hgrn_scan_phase(int wv, const P& p_, LAS unsigned char* lds, float* sumsq) {
;     ...
;       const int kx = tid & 127, seg = tid >> 7;
;       float bl[16];
;       { float run = 0.f;
; #pragma unroll
;         for (int i = 0; i < 16; ++i) { run += (float)LF[(16 * seg + i) * 128 + kx]; bl[i] = run; }
;         SEG[seg * 128 + kx] = run; }
;       lds_barrier();
;       { float pre = 0.f, blast = 0.f;
; #pragma unroll
;         for (int s2 = 0; s2 < 4; ++s2) { const float v = SEG[s2 * 128 + kx]; blast += v; if (s2 < seg) pre += v; }
;         u32x4 w0, w1; float kd[16];
; #pragma unroll
;         for (int i = 0; i < 16; ++i) { const float bc = pre + bl[i]; BC[(16 * seg + i) * 132 + kx] = bc; kd[i] = bf2f(Kr[(16 * seg + i) * 136 + kx]) * __builtin_amdgcn_exp2f(blast - bc); }
; #pragma unroll
;         for (int j = 0; j < 4; ++j) { w0[j] = pk2(kd[2 * j], kd[2 * j + 1]); w1[j] = pk2(kd[8 + 2 * j], kd[8 + 2 * j + 1]); }
;         *(LAS u32x4*)(KDT + kx * 72 + 16 * seg) = w0; *(LAS u32x4*)(KDT + kx * 72 + 16 * seg + 8) = w1;
;         if (seg == 0) DEC[kx] = __builtin_amdgcn_exp2f(blast); }
;       lds_barrier();
;       const int mt = wid >> 1, vt = wid & 1;
;       f32x4 oacc = (f32x4){0.f, 0.f, 0.f, 0.f}, a0 = oacc, a1 = oacc;
;       const int J0 = 2 * vt;
; #pragma unroll
;       for (int ks = 0; ks < 4; ++ks) {
;         const int kb = 32 * ks + 8 * fq, trow = 16 * mt + fr;
;         const bf16x8 qv = *(const LAS bf16x8*)(Q + trow * 136 + kb);
;         const f32x4 bc0 = *(const LAS f32x4*)(BC + trow * 132 + kb), bc1 = *(const LAS f32x4*)(BC + trow * 132 + kb + 4);
	s_cmp_eq_u32 s66, 0
	s_mov_b32 s0, 0x1f340000
	s_cselect_b32 s0, s0, 0x1f440000
	v_readlane_b32 s1, v255, 32
	s_add_u32 s67, s1, s0
	v_readlane_b32 s0, v255, 34
	v_readlane_b32 s4, v254, 27
	v_add_u32_e32 v4, 0x200, v0
	s_addc_u32 s79, s0, 0
	v_readlane_b32 s6, v254, 29
	v_readlane_b32 s7, v254, 30
	v_readlane_b32 s18, v254, 41
	s_movk_i32 s0, 0x880
	v_lshlrev_b32_e32 v5, 3, v0
	v_ashrrev_i32_e32 v82, 4, v4
	v_ashrrev_i32_e32 v4, 2, v0
	v_readlane_b32 s8, v254, 31
	v_readlane_b32 s9, v254, 32
	v_readlane_b32 s19, v254, 42
	s_add_u32 s24, s18, s22
	v_cmp_gt_i32_e64 s[6:7], s0, v0
	v_and_b32_e32 v78, 0x78, v5
	s_movk_i32 s0, 0x100
	v_and_b32_e32 v6, 24, v5
	v_ashrrev_i32_e32 v5, 31, v4
	v_readlane_b32 s10, v254, 33
	v_readlane_b32 s11, v254, 34
	s_addc_u32 s25, s19, s23
	v_cmp_gt_i32_e64 s[8:9], s0, v0
	s_movk_i32 s0, 0xff
	v_lshlrev_b64 v[8:9], 11, v[4:5]
	v_cmp_lt_i32_e64 s[10:11], s0, v0
	v_lshl_add_u64 v[10:11], s[24:25], 0, v[8:9]
	s_mov_b64 s[0:1], 0xf000000
	v_lshl_add_u64 v[86:87], v[10:11], 0, s[0:1]
	v_readlane_b32 s1, v254, 59
	v_ashrrev_i32_e32 v12, 7, v0
	v_readlane_b32 s5, v254, 28
	v_lshl_add_u32 v7, v4, 1, s1
	v_and_b32_e32 v4, 0x7f, v0
	v_and_b32_e32 v2, 15, v0
	v_lshlrev_b32_e32 v5, 1, v78
	v_readlane_b32 s0, v254, 58
	v_lshlrev_b32_e32 v11, 12, v12
	v_lshlrev_b32_e32 v13, 1, v4
	v_lshlrev_b32_e32 v15, 4, v12
	v_readlane_b32 s4, v254, 61
	v_ashrrev_i32_e32 v3, 6, v0
	s_mov_b32 s98, 0x20201020
	s_mov_b32 s99, 0x31133231
	v_lshlrev_b32_e32 v216, 2, v3
	v_lshrrev_b32_e64 v217, v216, s99
	v_lshrrev_b32_e64 v216, v216, s98
	v_and_b32_e32 v216, 3, v216
	v_and_b32_e32 v217, 3, v217
	v_add_u32_e32 v10, 0, v5
	v_add_u32_e32 v5, s0, v5
	v_add3_u32 v79, s0, v11, v13
	v_readlane_b32 s0, v254, 60
	v_lshlrev_b32_e32 v11, 2, v4
	v_mov_b32_e32 v16, s4
	v_readlane_b32 s5, v254, 62
	v_or_b32_e32 v20, v15, v2
	s_movk_i32 s27, 0x110
	v_bfe_u32 v1, v0, 4, 2
	v_lshlrev_b32_e32 v248, 2, v0
	v_add_u32_e32 v248, 0x1f600, v248
	v_lshlrev_b32_e32 v249, 9, v12
	v_lshl_add_u32 v249, v1, 5, v249
	v_add_u32_e32 v249, 0x1f600, v249
	v_add_u32_e32 v119, s0, v11
	v_add_u32_e32 v120, 0, v11
	v_mad_u32_u24 v16, v4, s90, v16
	v_add_u32_e32 v121, s5, v11
	v_and_b32_e32 v11, 1, v3
	v_mul_lo_u32 v4, v20, s27
	s_add_u32 s28, s24, 0x7000000
	v_add_u32_e32 v21, 0, v4
	v_lshlrev_b32_e32 v22, 8, v20
	v_lshlrev_b32_e32 v4, 4, v11
	v_mul_lo_u32 v20, v20, s90
	v_lshlrev_b32_e32 v26, 4, v1
	v_readlane_b32 s38, v255, 0
	s_addc_u32 s29, s25, 0
	v_or_b32_e32 v23, v4, v2
	v_add3_u32 v123, s38, v20, v26
	v_add_u32_e32 v20, s1, v26
	s_add_u32 s30, s24, 0xb000000
	v_lshlrev_b32_e32 v14, 2, v0
	v_mul_u32_u24_e32 v24, 0x110, v23
	v_mad_u32_u24 v124, v23, s90, v20
	v_and_b32_e32 v23, 0xffffffc0, v0
	s_addc_u32 s31, s25, 0
	v_ashrrev_i32_e32 v76, 4, v0
	v_add_u32_e32 v118, s0, v14
	v_lshlrev_b32_e32 v18, 1, v11
	s_movk_i32 s0, 0x2100
	v_lshl_or_b32 v25, v1, 2, v15
	v_add3_u32 v125, s5, v23, v26
	v_lshl_or_b32 v23, v3, 4, v2
	v_lshl_or_b32 v28, v216, 4, v2
	s_add_u32 s34, s24, 0x17000000
	v_mul_lo_u32 v122, v12, s0
	v_mul_lo_u32 v23, v23, s90
	v_mad_u64_u32 v[88:89], s[0:1], v76, s27, v[10:11]
	v_mad_u64_u32 v[90:91], s[0:1], v82, s27, v[10:11]
	v_cmp_gt_i32_e32 vcc, v216, v12
	v_cmp_gt_i32_e64 s[20:21], v28, v25
	v_or_b32_e32 v10, 1, v25
	s_addc_u32 s35, s25, 0
	v_add3_u32 v126, s4, v23, v26
	s_or_b64 s[4:5], vcc, s[20:21]
	v_cmp_gt_i32_e64 s[20:21], v28, v10
	v_or_b32_e32 v11, 2, v25
	s_or_b64 s[68:69], vcc, s[20:21]
	v_cmp_gt_i32_e64 s[20:21], v28, v11
	v_or_b32_e32 v89, 3, v25
	v_lshl_or_b32 v29, v217, 4, v2
	s_or_b64 s[72:73], vcc, s[20:21]
	v_cmp_gt_i32_e64 s[20:21], v28, v89
	v_readlane_b32 s12, v254, 35
	v_readlane_b32 s13, v254, 36
	v_lshlrev_b32_e32 v19, 3, v1
	v_cmp_gt_i32_e64 s[0:1], v217, v12
	s_or_b64 s[74:75], vcc, s[20:21]
	v_cmp_gt_i32_e32 vcc, v29, v25
	s_movk_i32 s36, 0x90
	s_movk_i32 s26, 0x1100
	v_lshlrev_b32_e32 v1, 5, v1
	v_cmp_gt_u32_e64 s[12:13], s96, v0
	s_or_b64 s[62:63], s[0:1], vcc
	v_cmp_gt_i32_e32 vcc, v29, v10
	v_mul_lo_u32 v30, v12, s26
	v_or_b32_e32 v10, 1, v15
	s_movk_i32 s26, 0x210
	v_add3_u32 v127, v21, v22, v1
	v_add3_u32 v128, 0, v122, v1
	v_mul_lo_u32 v25, v25, s36
	v_lshlrev_b32_e32 v1, 1, v29
	v_add_u32_e32 v134, 0xfffffe00, v0
	v_and_b32_e32 v0, 3, v0
	v_lshl_add_u64 v[8:9], s[22:23], 0, v[8:9]
	v_mul_lo_u32 v15, v10, s26
	v_mul_lo_u32 v31, v10, s27
	v_add3_u32 v130, s38, v25, v1
	v_lshlrev_b32_e32 v0, 4, v0
	v_mov_b32_e32 v1, v32
	v_readlane_b32 s26, v254, 14
	v_lshl_add_u64 v[0:1], v[8:9], 0, v[0:1]
	v_readlane_b32 s27, v254, 15
	v_lshlrev_b32_e32 v3, 5, v3
	v_readlane_b32 s37, v254, 63
	s_or_b64 s[82:83], s[0:1], vcc
	v_cmp_gt_i32_e32 vcc, v29, v11
	v_add_u32_e32 v91, v21, v26
	v_add_u32_e32 v21, 0, v26
	v_lshlrev_b32_e32 v10, 4, v2
	v_mov_b32_e32 v11, v32
	v_lshl_add_u64 v[94:95], s[26:27], 0, v[0:1]
	v_readlane_b32 s26, v252, 14
	v_readlane_b32 s14, v254, 37
	v_readlane_b32 s15, v254, 38
	v_readlane_b32 s16, v254, 39
	v_readlane_b32 s17, v254, 40
	v_ashrrev_i32_e32 v77, 31, v76
	v_ashrrev_i32_e32 v83, 31, v82
	v_sub_u32_e32 v13, v120, v13
	v_lshlrev_b32_e32 v17, 5, v12
	v_add3_u32 v3, s37, v3, v19
	v_lshlrev_b32_e32 v19, 8, v76
	v_lshlrev_b32_e32 v23, 8, v82
	v_mul_u32_u24_e32 v27, 0x90, v6
	s_or_b64 s[90:91], s[0:1], vcc
	v_cmp_gt_i32_e32 vcc, v29, v89
	v_add3_u32 v129, s37, v24, v26
	v_add_u32_e32 v22, v21, v26
	v_lshl_add_u64 v[92:93], s[24:25], 0, v[10:11]
	v_mul_u32_u24_e32 v10, 0x110, v28
	v_mul_u32_u24_e32 v11, 0x210, v28
	v_lshl_add_u32 v24, v28, 1, s38
	v_mul_u32_u24_e32 v26, 0x90, v2
	v_mul_u32_u24_e32 v28, 0x110, v2
	v_readlane_b32 s27, v252, 15
	v_lshlrev_b64 v[80:81], 10, v[76:77]
	v_lshlrev_b64 v[84:85], 10, v[82:83]
	v_cmp_eq_u32_e64 s[14:15], 0, v2
	v_cmp_lt_i32_e64 s[16:17], 0, v12
	v_cmp_lt_i32_e64 s[18:19], 1, v12
	s_or_b64 s[0:1], s[0:1], vcc
	v_cmp_lt_i32_e64 s[20:21], 2, v12
	v_cmp_lt_i32_e64 s[22:23], 3, v12
	v_cmp_le_i32_e64 s[24:25], v216, v12
	v_add_u32_e32 v131, 0x90, v130
	v_add_u32_e32 v132, 0x120, v130
	v_add_u32_e32 v133, 0x1b0, v130
	v_add_u32_e32 v135, s37, v14
	v_lshlrev_b32_e32 v96, 1, v6
	s_waitcnt vmcnt(9)
	v_lshlrev_b32_e32 v98, 1, v4
	v_lshlrev_b32_e32 v100, 1, v2
	v_add_u32_e32 v136, v5, v19
	v_add_u32_e32 v137, v5, v23
	v_add_u32_e32 v138, v7, v27
	v_add_u32_e32 v139, v13, v30
	v_add_u32_e32 v140, v120, v15
	v_add_u32_e32 v141, v13, v31
	v_add_u32_e32 v142, v16, v17
	v_add_u32_e32 v143, v24, v25
	v_add_u32_e32 v144, v20, v26
	v_add_u32_e32 v145, v3, v28
	v_add_u32_e32 v146, v21, v10
	v_add_u32_e32 v147, v22, v11
	v_mul_u32_u24_e32 v218, 0x110, v29
	v_mul_u32_u24_e32 v219, 0x210, v29
	v_add_u32_e32 v218, 0xffffef00, v218
	v_add_u32_e32 v219, 0xffffdf00, v219
	v_add_u32_e32 v218, v21, v218
	v_add_u32_e32 v219, v22, v219
	v_readlane_b32 s54, v254, 12
	s_mov_b32 s57, s26
	v_cmp_le_i32_e64 s[26:27], v217, v12
	s_branch .LBB0_433

; #define LAS __attribute__((address_space(3)))
; DI unsigned pk2(float a, float b) { typedef __bf16 bf2 __attribute__((ext_vector_type(2))); bf2 v; v[0] = (__bf16)a; v[1] = (__bf16)b; return __builtin_bit_cast(unsigned, v); }
; DI float bf2f(bf16_t v) { return __uint_as_float(((unsigned)v) << 16); }
; DI void lds_barrier() { asm volatile("s_waitcnt lgkmcnt(0)\n\ts_barrier" ::: "memory"); }
; DI void hgrn_scan_phase(int wv, const P& p_, LAS unsigned char* lds, float* sumsq) {
;     ...
;       const int kx = tid & 127, seg = tid >> 7;
;       float bl[16];
;       { float run = 0.f;
; #pragma unroll
;         for (int i = 0; i < 16; ++i) { run += (float)LF[(16 * seg + i) * 128 + kx]; bl[i] = run; }
;         SEG[seg * 128 + kx] = run; }
;       lds_barrier();
;       { float pre = 0.f, blast = 0.f;
; #pragma unroll
;         for (int s2 = 0; s2 < 4; ++s2) { const float v = SEG[s2 * 128 + kx]; blast += v; if (s2 < seg) pre += v; }
;         u32x4 w0, w1; float kd[16];
; #pragma unroll
;         for (int i = 0; i < 16; ++i) { const float bc = pre + bl[i]; BC[(16 * seg + i) * 132 + kx] = bc; kd[i] = bf2f(Kr[(16 * seg + i) * 136 + kx]) * __builtin_amdgcn_exp2f(blast - bc); }
; #pragma unroll
;         for (int j = 0; j < 4; ++j) { w0[j] = pk2(kd[2 * j], kd[2 * j + 1]); w1[j] = pk2(kd[8 + 2 * j], kd[8 + 2 * j + 1]); }
;         *(LAS u32x4*)(KDT + kx * 72 + 16 * seg) = w0; *(LAS u32x4*)(KDT + kx * 72 + 16 * seg + 8) = w1;
;         if (seg == 0) DEC[kx] = __builtin_amdgcn_exp2f(blast); }
;       lds_barrier();
.LBB0_448:
	s_waitcnt lgkmcnt(0)
	s_barrier
	ds_read_u16 v33, v79
	ds_read_u16 v34, v79 offset:256
	ds_read_u16 v35, v79 offset:512
	ds_read_u16 v40, v79 offset:768
	ds_read_u16 v41, v79 offset:1024
	ds_read_u16 v42, v79 offset:1280
	ds_read_u16 v43, v79 offset:1536
	ds_read_u16 v44, v79 offset:1792
	s_waitcnt lgkmcnt(7)
	v_cvt_f32_f16_e32 v33, v33
	s_waitcnt lgkmcnt(6)
	v_cvt_f32_f16_e32 v34, v34
	s_waitcnt lgkmcnt(5)
	v_cvt_f32_f16_e32 v35, v35
	s_waitcnt lgkmcnt(4)
	v_cvt_f32_f16_e32 v40, v40
	v_add_f32_e32 v33, 0, v33
	v_add_f32_e32 v45, v33, v34
	s_waitcnt lgkmcnt(3)
	v_cvt_f32_f16_e32 v34, v41
	v_add_f32_e32 v46, v45, v35
	s_waitcnt lgkmcnt(2)
	v_cvt_f32_f16_e32 v35, v42
	v_add_f32_e32 v47, v46, v40
	s_waitcnt lgkmcnt(1)
	v_cvt_f32_f16_e32 v40, v43
	s_waitcnt lgkmcnt(0)
	v_cvt_f32_f16_e32 v41, v44
	v_add_f32_e32 v44, v47, v34
	v_add_f32_e32 v49, v44, v35
	v_add_f32_e32 v50, v49, v40
	v_add_f32_e32 v51, v50, v41
	ds_read_u16 v34, v79 offset:2048
	ds_read_u16 v35, v79 offset:2304
	ds_read_u16 v40, v79 offset:2560
	ds_read_u16 v41, v79 offset:2816
	ds_read_u16 v42, v79 offset:3072
	ds_read_u16 v43, v79 offset:3328
	ds_read_u16 v48, v79 offset:3584
	ds_read_u16 v52, v79 offset:3840
	s_waitcnt lgkmcnt(7)
	v_cvt_f32_f16_e32 v34, v34
	s_waitcnt lgkmcnt(6)
	v_cvt_f32_f16_e32 v35, v35
	s_waitcnt lgkmcnt(5)
	v_cvt_f32_f16_e32 v40, v40
	s_waitcnt lgkmcnt(4)
	v_cvt_f32_f16_e32 v41, v41
	v_add_f32_e32 v53, v51, v34
	s_waitcnt lgkmcnt(3)
	v_cvt_f32_f16_e32 v34, v42
	v_add_f32_e32 v54, v53, v35
	s_waitcnt lgkmcnt(2)
	v_cvt_f32_f16_e32 v35, v43
	v_add_f32_e32 v55, v54, v40
	s_waitcnt lgkmcnt(1)
	v_cvt_f32_f16_e32 v40, v48
	v_add_f32_e32 v56, v55, v41
	s_waitcnt lgkmcnt(0)
	v_cvt_f32_f16_e32 v41, v52
	v_add_f32_e32 v57, v56, v34
	v_add_f32_e32 v58, v57, v35
	v_add_f32_e32 v59, v58, v40
	v_add_f32_e32 v35, v59, v41
	ds_write_b32 v118, v35
	s_waitcnt lgkmcnt(0)
	s_barrier
	ds_read2st64_b32 v[40:41], v119 offset1:2
	ds_read2st64_b32 v[42:43], v119 offset0:4 offset1:6
	v_add_u32_e32 v52, 0x9800, v140
	s_waitcnt lgkmcnt(1)
	v_add_f32_e32 v34, 0, v40
	v_cndmask_b32_e64 v40, 0, v34, s[16:17]
	v_add_f32_e32 v34, v34, v41
	v_add_f32_e32 v41, v41, v40
	v_cndmask_b32_e64 v40, v40, v41, s[18:19]
	s_waitcnt lgkmcnt(0)
	v_add_f32_e32 v41, v42, v40
	v_cndmask_b32_e64 v40, v40, v41, s[20:21]
	v_add_f32_e32 v41, v43, v40
	v_cndmask_b32_e64 v41, v40, v41, s[22:23]
	v_add_f32_e32 v33, v33, v41
	v_add_u32_e32 v40, v120, v122
	v_add_f32_e32 v34, v34, v42
	ds_write_b32 v40, v33 offset:34816
	v_exp_f32_e32 v231, v33
	v_mov_b32_e32 v40, v43
	v_pk_add_f32 v[34:35], v[34:35], v[40:41]
	s_nop 0
	v_sub_f32_e32 v33, v34, v33
	ds_write_b32 v248, v231
	v_exp_f32_e32 v42, v33
	v_add_f32_e32 v33, v45, v41
	v_sub_f32_e32 v40, v34, v33
	v_exp_f32_e32 v43, v40
	v_add_f32_e32 v40, v46, v41
	v_add_u32_e32 v45, 0x8800, v140
	ds_write2_b32 v45, v33, v40 offset1:132
	v_sub_f32_e32 v33, v34, v40
	v_exp_f32_e32 v46, v33
	v_add_f32_e32 v33, v47, v41
	v_sub_f32_e32 v40, v34, v33
	v_exp_f32_e32 v47, v40
	v_add_f32_e32 v40, v44, v41
	v_add_u32_e32 v44, 0x8c00, v140
	ds_write2_b32 v44, v33, v40 offset0:8 offset1:140
	v_sub_f32_e32 v33, v34, v40
	v_exp_f32_e32 v48, v33
	v_add_f32_e32 v33, v49, v41
	v_sub_f32_e32 v40, v34, v33
	v_exp_f32_e32 v49, v40
	v_add_f32_e32 v40, v50, v41
	v_add_u32_e32 v44, 0x9000, v140
	ds_write2_b32 v44, v33, v40 offset0:16 offset1:148
	v_sub_f32_e32 v33, v34, v40
	v_exp_f32_e32 v50, v33
	v_add_f32_e32 v33, v51, v41
	v_sub_f32_e32 v40, v34, v33
	v_exp_f32_e32 v51, v40
	v_add_f32_e32 v40, v53, v41
	v_add_u32_e32 v44, 0x9400, v140
	ds_read_u16 v60, v139 offset:17408
	ds_read_u16 v61, v141 offset:17408
	ds_read_u16 v62, v141 offset:17680
	ds_read_u16 v63, v141 offset:17952
	ds_read_u16 v64, v141 offset:18224
	ds_read_u16 v65, v141 offset:18496
	ds_read_u16 v66, v141 offset:18768
	ds_read_u16 v67, v141 offset:19040
	ds_write2_b32 v44, v33, v40 offset0:24 offset1:156
	v_sub_f32_e32 v33, v34, v40
	v_exp_f32_e32 v44, v33
	v_add_f32_e32 v33, v54, v41
	v_sub_f32_e32 v40, v34, v33
	v_exp_f32_e32 v45, v40
	v_add_f32_e32 v40, v55, v41
	ds_write2_b32 v52, v33, v40 offset0:32 offset1:164
	v_sub_f32_e32 v33, v34, v40
	v_exp_f32_e32 v52, v33
	v_add_f32_e32 v33, v56, v41
	v_sub_f32_e32 v40, v34, v33
	v_exp_f32_e32 v53, v40
	v_add_f32_e32 v40, v57, v41
	v_add_u32_e32 v54, 0x9c00, v140
	ds_write2_b32 v54, v33, v40 offset0:40 offset1:172
	v_sub_f32_e32 v33, v34, v40
	v_exp_f32_e32 v54, v33
	v_add_f32_e32 v33, v58, v41
	v_sub_f32_e32 v40, v34, v33
	v_exp_f32_e32 v55, v40
	v_add_f32_e32 v40, v59, v41
	v_add_u32_e32 v41, 0xa000, v140
	ds_write2_b32 v41, v33, v40 offset0:48 offset1:180
	v_sub_f32_e32 v33, v34, v40
	v_exp_f32_e32 v56, v33
	ds_write_b32 v140, v35 offset:42208
	v_sub_f32_e32 v33, v34, v35
	s_waitcnt lgkmcnt(11)
	v_lshlrev_b32_e32 v41, 16, v61
	v_lshlrev_b32_e32 v40, 16, v60
	v_exp_f32_e32 v57, v33
	v_pk_mul_f32 v[40:41], v[42:43], v[40:41]
	ds_read_u16 v33, v141 offset:19312
	ds_read_u16 v35, v141 offset:19584
	ds_read_u16 v58, v141 offset:19856
	ds_read_u16 v59, v141 offset:20128
	ds_read_u16 v60, v141 offset:20400
	ds_read_u16 v61, v141 offset:20672
	ds_read_u16 v68, v141 offset:20944
	ds_read_u16 v69, v141 offset:21216
	s_waitcnt lgkmcnt(7)
	v_lshlrev_b32_e32 v42, 16, v33
	s_waitcnt lgkmcnt(6)
	v_lshlrev_b32_e32 v43, 16, v35
	v_pk_mul_f32 v[42:43], v[44:45], v[42:43]
	v_cvt_pk_bf16_f32 v40, v40, v41
	v_cvt_pk_bf16_f32 v44, v42, v43
	v_lshlrev_b32_e32 v43, 16, v63
	v_lshlrev_b32_e32 v42, 16, v62
	v_pk_mul_f32 v[42:43], v[46:47], v[42:43]
	s_waitcnt lgkmcnt(3)
	v_lshlrev_b32_e32 v46, 16, v60
	v_cvt_pk_bf16_f32 v41, v42, v43
	v_lshlrev_b32_e32 v42, 16, v58
	v_lshlrev_b32_e32 v43, 16, v59
	v_pk_mul_f32 v[42:43], v[52:53], v[42:43]
	s_waitcnt lgkmcnt(2)
	v_lshlrev_b32_e32 v47, 16, v61
	v_cvt_pk_bf16_f32 v45, v42, v43
	v_lshlrev_b32_e32 v43, 16, v65
	v_lshlrev_b32_e32 v42, 16, v64
	v_pk_mul_f32 v[42:43], v[48:49], v[42:43]
	v_lshlrev_b32_e32 v48, 16, v66
	v_lshlrev_b32_e32 v49, 16, v67
	v_pk_mul_f32 v[48:49], v[50:51], v[48:49]
	v_cvt_pk_bf16_f32 v42, v42, v43
	v_cvt_pk_bf16_f32 v43, v48, v49
	s_waitcnt lgkmcnt(1)
	v_lshlrev_b32_e32 v48, 16, v68
	s_waitcnt lgkmcnt(0)
	v_lshlrev_b32_e32 v49, 16, v69
	v_pk_mul_f32 v[46:47], v[54:55], v[46:47]
	v_pk_mul_f32 v[48:49], v[56:57], v[48:49]
	v_cvt_pk_bf16_f32 v46, v46, v47
	v_cvt_pk_bf16_f32 v47, v48, v49
	ds_write_b128 v142, v[40:43]
	ds_write_b128 v142, v[44:47] offset:16
	s_and_saveexec_b64 vcc, s[12:13]
	v_exp_f32_e32 v33, v34
	ds_write_b32 v121, v33
	s_or_b64 exec, exec, vcc
	s_waitcnt lgkmcnt(0)
	s_barrier
; DI void hgrn_scan_phase(int wv, const P& p_, LAS unsigned char* lds, float* sumsq) {
;     ...
;       for (int ks = 0; ks < 4; ++ks) {
;         const int kb = 32 * ks + 8 * fq, trow = 16 * mt + fr;
;         const bf16x8 qv = *(const LAS bf16x8*)(Q + trow * 136 + kb);
;         const f32x4 bc0 = *(const LAS f32x4*)(BC + trow * 132 + kb), bc1 = *(const LAS f32x4*)(BC + trow * 132 + kb + 4);
;         const f32x4 r0 = *(const LAS f32x4*)(BC + (16 * mt) * 132 + kb), r1 = *(const LAS f32x4*)(BC + (16 * mt) * 132 + kb + 4);
;         u32x4 ai, aq;
; #pragma unroll
;         for (int j = 0; j < 4; ++j) {
;           const float q0 = bf2f((bf16_t)qv[2 * j]), q1 = bf2f((bf16_t)qv[2 * j + 1]);
;           const float b0 = j < 2 ? bc0[2 * j] : bc1[2 * j - 4], b1 = j < 2 ? bc0[2 * j + 1] : bc1[2 * j - 3];
;           const float rr0 = j < 2 ? r0[2 * j] : r1[2 * j - 4], rr1 = j < 2 ? r0[2 * j + 1] : r1[2 * j - 3];
;           ai[j] = pk2(q0 * __builtin_amdgcn_exp2f(b0), q1 * __builtin_amdgcn_exp2f(b1)); aq[j] = pk2(q0 * __builtin_amdgcn_exp2f(b0 - rr0), q1 * __builtin_amdgcn_exp2f(b1 - rr1));
;         }
;         const bf16x8 sb = *(const LAS bf16x8*)(ST + (16 * vt + fr) * 136 + kb);
;         oacc = MFMA16(__builtin_bit_cast(bf16x8, ai), sb, oacc);
; #pragma unroll
;         for (int jj = 0; jj < 2; ++jj) {
;           const int J = J0 + jj; if (J > mt) continue;
;           const int srow = 16 * J + fr;
;           const bf16x8 kv = *(const LAS bf16x8*)(Kr + srow * 136 + kb);
;           const f32x4 c0 = *(const LAS f32x4*)(BC + srow * 132 + kb), c1 = *(const LAS f32x4*)(BC + srow * 132 + kb + 4);
;           u32x4 bk;
; #pragma unroll
;           for (int j = 0; j < 4; ++j) {
;             const float k0 = bf2f((bf16_t)kv[2 * j]), k1 = bf2f((bf16_t)kv[2 * j + 1]);
;             const float b0 = j < 2 ? c0[2 * j] : c1[2 * j - 4], b1 = j < 2 ? c0[2 * j + 1] : c1[2 * j - 3];
;             const float rr0 = j < 2 ? r0[2 * j] : r1[2 * j - 4], rr1 = j < 2 ? r0[2 * j + 1] : r1[2 * j - 3];
;             bk[j] = pk2(k0 * __builtin_amdgcn_exp2f(fminf(rr0 - b0, 115.f)), k1 * __builtin_amdgcn_exp2f(fminf(rr1 - b1, 115.f)));
;           }
;           if (jj == 0) a0 = MFMA16(__builtin_bit_cast(bf16x8, aq), __builtin_bit_cast(bf16x8, bk), a0);
;           else a1 = MFMA16(__builtin_bit_cast(bf16x8, aq), __builtin_bit_cast(bf16x8, bk), a1);
	ds_read_b128 v[220:223], v249
	ds_read_b128 v[224:227], v249 offset:16
	ds_read_b128 v[40:43], v91
	ds_read_b128 v[52:55], v127 offset:34816
	ds_read_b128 v[48:51], v127 offset:34832
	ds_read_b128 v[64:67], v128 offset:34816
	ds_read_b128 v[56:59], v128 offset:34832
	s_waitcnt lgkmcnt(4)
	v_and_b32_e32 v115, 0xffff0000, v40
	v_lshlrev_b32_e32 v114, 16, v40
	v_and_b32_e32 v113, 0xffff0000, v41
	s_waitcnt lgkmcnt(1)
	v_sub_f32_e32 v33, v52, v64
	v_exp_f32_e32 v34, v33
	v_sub_f32_e32 v33, v53, v65
	v_exp_f32_e32 v35, v33
	v_sub_f32_e32 v33, v54, v66
	v_lshlrev_b32_e32 v112, 16, v41
	v_and_b32_e32 v75, 0xffff0000, v42
	v_pk_mul_f32 v[34:35], v[34:35], v[114:115]
	v_lshlrev_b32_e32 v74, 16, v42
	v_pk_mul_f32 v[230:231], v[34:35], v[220:221]
	v_cvt_pk_bf16_f32 v60, v34, v35
	v_cvt_pk_bf16_f32 v244, v230, v231
	v_exp_f32_e32 v34, v33
	v_sub_f32_e32 v33, v55, v67
	v_exp_f32_e32 v35, v33
	s_waitcnt lgkmcnt(0)
	v_sub_f32_e32 v33, v48, v56
	v_and_b32_e32 v73, 0xffff0000, v43
	v_lshlrev_b32_e32 v72, 16, v43
	v_pk_mul_f32 v[34:35], v[34:35], v[112:113]
	ds_read_b128 v[68:71], v129
	v_pk_mul_f32 v[230:231], v[34:35], v[222:223]
	v_cvt_pk_bf16_f32 v61, v34, v35
	v_cvt_pk_bf16_f32 v245, v230, v231
	v_exp_f32_e32 v34, v33
	v_sub_f32_e32 v33, v49, v57
	v_exp_f32_e32 v35, v33
	v_sub_f32_e32 v33, v50, v58
	v_pk_mul_f32 v[34:35], v[34:35], v[74:75]
	s_nop 0
	v_pk_mul_f32 v[230:231], v[34:35], v[224:225]
	v_cvt_pk_bf16_f32 v62, v34, v35
	v_cvt_pk_bf16_f32 v246, v230, v231
	v_exp_f32_e32 v34, v33
	v_sub_f32_e32 v33, v51, v59
	v_exp_f32_e32 v35, v33
	v_mov_b32_e32 v33, v32
	v_pk_mul_f32 v[34:35], v[34:35], v[72:73]
	s_nop 0
	v_pk_mul_f32 v[230:231], v[34:35], v[226:227]
	v_cvt_pk_bf16_f32 v63, v34, v35
	v_cvt_pk_bf16_f32 v247, v230, v231
	v_mov_b32_e32 v34, v32
	v_mov_b32_e32 v35, v32
	v_mov_b64_e32 v[42:43], v[34:35]
	v_mov_b64_e32 v[40:41], v[32:33]
	s_and_saveexec_b64 vcc, s[24:25]
	s_cbranch_execz .LBB0_452
	ds_read_b128 v[40:43], v147 offset:34816
	ds_read_b128 v[44:47], v146 offset:17408
	ds_read_b128 v[148:151], v147 offset:34832
	s_waitcnt lgkmcnt(2)
	v_sub_f32_e32 v40, v64, v40
	v_sub_f32_e32 v41, v65, v41
	v_min_f32_e32 v40, 0x42e60000, v40
	v_min_f32_e32 v41, 0x42e60000, v41
	v_exp_f32_e32 v40, v40
	v_exp_f32_e32 v41, v41
	s_waitcnt lgkmcnt(1)
	v_and_b32_e32 v117, 0xffff0000, v44
	v_lshlrev_b32_e32 v116, 16, v44
	v_sub_f32_e32 v42, v66, v42
	v_pk_mul_f32 v[40:41], v[40:41], v[116:117]
	v_sub_f32_e32 v43, v67, v43
	v_cvt_pk_bf16_f32 v40, v40, v41
	s_waitcnt lgkmcnt(0)
	v_sub_f32_e32 v41, v56, v148
	v_min_f32_e32 v42, 0x42e60000, v42
	v_min_f32_e32 v43, 0x42e60000, v43
	v_min_f32_e32 v41, 0x42e60000, v41
	v_exp_f32_e32 v42, v42
	v_exp_f32_e32 v43, v43
	v_exp_f32_e32 v44, v41
	v_sub_f32_e32 v41, v57, v149
	v_min_f32_e32 v41, 0x42e60000, v41
	v_and_b32_e32 v117, 0xffff0000, v45
	v_lshlrev_b32_e32 v116, 16, v45
	v_exp_f32_e32 v45, v41
	v_pk_mul_f32 v[42:43], v[42:43], v[116:117]
	v_and_b32_e32 v117, 0xffff0000, v47
	v_cvt_pk_bf16_f32 v41, v42, v43
	v_and_b32_e32 v43, 0xffff0000, v46
	v_lshlrev_b32_e32 v42, 16, v46
	v_pk_mul_f32 v[42:43], v[44:45], v[42:43]
	v_sub_f32_e32 v44, v58, v150
	v_sub_f32_e32 v45, v59, v151
	v_min_f32_e32 v44, 0x42e60000, v44
	v_min_f32_e32 v45, 0x42e60000, v45
	v_exp_f32_e32 v44, v44
	v_exp_f32_e32 v45, v45
	v_lshlrev_b32_e32 v116, 16, v47
	v_cvt_pk_bf16_f32 v42, v42, v43
	v_pk_mul_f32 v[44:45], v[44:45], v[116:117]
	s_nop 0
	v_cvt_pk_bf16_f32 v43, v44, v45
	s_nop 1
	v_mfma_f32_16x16x32_bf16 v[40:43], v[60:63], v[40:43], 0

; DI void hgrn_scan_phase(int wv, const P& p_, LAS unsigned char* lds, float* sumsq) {
;     ...
;       for (int ks = 0; ks < 4; ++ks) {
;         const int kb = 32 * ks + 8 * fq, trow = 16 * mt + fr;
;         const bf16x8 qv = *(const LAS bf16x8*)(Q + trow * 136 + kb);
;         const f32x4 bc0 = *(const LAS f32x4*)(BC + trow * 132 + kb), bc1 = *(const LAS f32x4*)(BC + trow * 132 + kb + 4);
;         const f32x4 r0 = *(const LAS f32x4*)(BC + (16 * mt) * 132 + kb), r1 = *(const LAS f32x4*)(BC + (16 * mt) * 132 + kb + 4);
;         u32x4 ai, aq;
; #pragma unroll
;         for (int j = 0; j < 4; ++j) {
;           const float q0 = bf2f((bf16_t)qv[2 * j]), q1 = bf2f((bf16_t)qv[2 * j + 1]);
;           const float b0 = j < 2 ? bc0[2 * j] : bc1[2 * j - 4], b1 = j < 2 ? bc0[2 * j + 1] : bc1[2 * j - 3];
;           const float rr0 = j < 2 ? r0[2 * j] : r1[2 * j - 4], rr1 = j < 2 ? r0[2 * j + 1] : r1[2 * j - 3];
;           ai[j] = pk2(q0 * __builtin_amdgcn_exp2f(b0), q1 * __builtin_amdgcn_exp2f(b1)); aq[j] = pk2(q0 * __builtin_amdgcn_exp2f(b0 - rr0), q1 * __builtin_amdgcn_exp2f(b1 - rr1));
;         }
;         const bf16x8 sb = *(const LAS bf16x8*)(ST + (16 * vt + fr) * 136 + kb);
;         oacc = MFMA16(__builtin_bit_cast(bf16x8, ai), sb, oacc);
; #pragma unroll
;         for (int jj = 0; jj < 2; ++jj) {
;           const int J = J0 + jj; if (J > mt) continue;
;           const int srow = 16 * J + fr;
;           const bf16x8 kv = *(const LAS bf16x8*)(Kr + srow * 136 + kb);
;           const f32x4 c0 = *(const LAS f32x4*)(BC + srow * 132 + kb), c1 = *(const LAS f32x4*)(BC + srow * 132 + kb + 4);
;           u32x4 bk;
; #pragma unroll
;           for (int j = 0; j < 4; ++j) {
;             const float k0 = bf2f((bf16_t)kv[2 * j]), k1 = bf2f((bf16_t)kv[2 * j + 1]);
;             const float b0 = j < 2 ? c0[2 * j] : c1[2 * j - 4], b1 = j < 2 ? c0[2 * j + 1] : c1[2 * j - 3];
;             const float rr0 = j < 2 ? r0[2 * j] : r1[2 * j - 4], rr1 = j < 2 ? r0[2 * j + 1] : r1[2 * j - 3];
;             bk[j] = pk2(k0 * __builtin_amdgcn_exp2f(fminf(rr0 - b0, 115.f)), k1 * __builtin_amdgcn_exp2f(fminf(rr1 - b1, 115.f)));
;           }
;           if (jj == 0) a0 = MFMA16(__builtin_bit_cast(bf16x8, aq), __builtin_bit_cast(bf16x8, bk), a0);
;           else a1 = MFMA16(__builtin_bit_cast(bf16x8, aq), __builtin_bit_cast(bf16x8, bk), a1);
.LBB0_454:
	s_or_b64 exec, exec, vcc
	s_waitcnt lgkmcnt(0)
	s_nop 0
	v_mfma_f32_16x16x32_bf16 v[48:51], v[244:247], v[68:71], 0
	ds_read_b128 v[220:223], v249 offset:128
	ds_read_b128 v[224:227], v249 offset:144
	ds_read_b128 v[64:67], v91 offset:64
	ds_read_b128 v[56:59], v127 offset:34944
	ds_read_b128 v[52:55], v127 offset:34960
	ds_read_b128 v[68:71], v128 offset:34944
	ds_read_b128 v[60:63], v128 offset:34960
	s_waitcnt lgkmcnt(4)
	v_and_b32_e32 v117, 0xffff0000, v64
	v_lshlrev_b32_e32 v116, 16, v64
	v_and_b32_e32 v115, 0xffff0000, v65
	s_waitcnt lgkmcnt(1)
	v_sub_f32_e32 v33, v56, v68
	v_exp_f32_e32 v34, v33
	v_sub_f32_e32 v33, v57, v69
	v_exp_f32_e32 v35, v33
	v_sub_f32_e32 v33, v58, v70
	v_lshlrev_b32_e32 v114, 16, v65
	v_and_b32_e32 v113, 0xffff0000, v66
	v_pk_mul_f32 v[34:35], v[34:35], v[116:117]
	v_lshlrev_b32_e32 v112, 16, v66
	v_pk_mul_f32 v[230:231], v[34:35], v[220:221]
	v_cvt_pk_bf16_f32 v64, v34, v35
	v_cvt_pk_bf16_f32 v244, v230, v231
	v_exp_f32_e32 v34, v33
	v_sub_f32_e32 v33, v59, v71
	v_exp_f32_e32 v35, v33
	s_waitcnt lgkmcnt(0)
	v_sub_f32_e32 v33, v52, v60
	v_pk_mul_f32 v[34:35], v[34:35], v[114:115]
	s_nop 0
	v_pk_mul_f32 v[230:231], v[34:35], v[222:223]
	v_cvt_pk_bf16_f32 v65, v34, v35
	v_cvt_pk_bf16_f32 v245, v230, v231
	v_exp_f32_e32 v34, v33
	v_sub_f32_e32 v33, v53, v61
	v_exp_f32_e32 v35, v33
	v_sub_f32_e32 v33, v54, v62
	v_exp_f32_e32 v72, v33
	v_sub_f32_e32 v33, v55, v63
	v_exp_f32_e32 v73, v33
	v_pk_mul_f32 v[34:35], v[34:35], v[112:113]
	s_nop 0
	v_pk_mul_f32 v[230:231], v[34:35], v[224:225]
	v_cvt_pk_bf16_f32 v66, v34, v35
	v_cvt_pk_bf16_f32 v246, v230, v231
	v_and_b32_e32 v35, 0xffff0000, v67
	v_lshlrev_b32_e32 v34, 16, v67
	v_pk_mul_f32 v[72:73], v[72:73], v[34:35]
	s_nop 0
	v_pk_mul_f32 v[230:231], v[72:73], v[226:227]
	v_cvt_pk_bf16_f32 v67, v72, v73
	v_cvt_pk_bf16_f32 v247, v230, v231
	ds_read_b128 v[72:75], v129 offset:64
	s_and_saveexec_b64 vcc, s[24:25]
	s_cbranch_execz .LBB0_456
	ds_read_b128 v[148:151], v147 offset:34944
	ds_read_b128 v[152:155], v146 offset:17472
	ds_read_b128 v[156:159], v147 offset:34960
	s_waitcnt lgkmcnt(2)
	v_sub_f32_e32 v33, v68, v148
	v_min_f32_e32 v33, 0x42e60000, v33
	v_exp_f32_e32 v148, v33
	v_sub_f32_e32 v33, v70, v150
	v_min_f32_e32 v33, 0x42e60000, v33
	v_sub_f32_e32 v97, v69, v149
	v_exp_f32_e32 v150, v33
	v_sub_f32_e32 v33, v71, v151
	v_min_f32_e32 v97, 0x42e60000, v97
	v_min_f32_e32 v33, 0x42e60000, v33
	v_exp_f32_e32 v149, v97
	v_exp_f32_e32 v151, v33
	s_waitcnt lgkmcnt(0)
	v_sub_f32_e32 v33, v60, v156
	v_min_f32_e32 v33, 0x42e60000, v33
	v_and_b32_e32 v161, 0xffff0000, v152
	v_lshlrev_b32_e32 v160, 16, v152
	v_exp_f32_e32 v152, v33
	v_sub_f32_e32 v33, v61, v157
	v_min_f32_e32 v33, 0x42e60000, v33
	v_pk_mul_f32 v[148:149], v[148:149], v[160:161]
	v_and_b32_e32 v161, 0xffff0000, v153
	v_lshlrev_b32_e32 v160, 16, v153
	v_exp_f32_e32 v153, v33
	v_pk_mul_f32 v[150:151], v[150:151], v[160:161]
	v_sub_f32_e32 v33, v62, v158
	v_cvt_pk_bf16_f32 v148, v148, v149
	v_cvt_pk_bf16_f32 v149, v150, v151
	v_and_b32_e32 v151, 0xffff0000, v154
	v_lshlrev_b32_e32 v150, 16, v154
	v_min_f32_e32 v33, 0x42e60000, v33
	v_pk_mul_f32 v[150:151], v[152:153], v[150:151]
	v_exp_f32_e32 v152, v33
	v_sub_f32_e32 v33, v63, v159
	v_min_f32_e32 v33, 0x42e60000, v33
	v_exp_f32_e32 v153, v33
	v_and_b32_e32 v157, 0xffff0000, v155
	v_lshlrev_b32_e32 v156, 16, v155
	v_cvt_pk_bf16_f32 v150, v150, v151
	v_pk_mul_f32 v[152:153], v[152:153], v[156:157]
	s_nop 0
	v_cvt_pk_bf16_f32 v151, v152, v153
	s_nop 1
	v_mfma_f32_16x16x32_bf16 v[40:43], v[64:67], v[148:151], v[40:43]

; DI void hgrn_scan_phase(int wv, const P& p_, LAS unsigned char* lds, float* sumsq) {
;     ...
;       for (int ks = 0; ks < 4; ++ks) {
;         const int kb = 32 * ks + 8 * fq, trow = 16 * mt + fr;
;         const bf16x8 qv = *(const LAS bf16x8*)(Q + trow * 136 + kb);
;         const f32x4 bc0 = *(const LAS f32x4*)(BC + trow * 132 + kb), bc1 = *(const LAS f32x4*)(BC + trow * 132 + kb + 4);
;         const f32x4 r0 = *(const LAS f32x4*)(BC + (16 * mt) * 132 + kb), r1 = *(const LAS f32x4*)(BC + (16 * mt) * 132 + kb + 4);
;         u32x4 ai, aq;
; #pragma unroll
;         for (int j = 0; j < 4; ++j) {
;           const float q0 = bf2f((bf16_t)qv[2 * j]), q1 = bf2f((bf16_t)qv[2 * j + 1]);
;           const float b0 = j < 2 ? bc0[2 * j] : bc1[2 * j - 4], b1 = j < 2 ? bc0[2 * j + 1] : bc1[2 * j - 3];
;           const float rr0 = j < 2 ? r0[2 * j] : r1[2 * j - 4], rr1 = j < 2 ? r0[2 * j + 1] : r1[2 * j - 3];
;           ai[j] = pk2(q0 * __builtin_amdgcn_exp2f(b0), q1 * __builtin_amdgcn_exp2f(b1)); aq[j] = pk2(q0 * __builtin_amdgcn_exp2f(b0 - rr0), q1 * __builtin_amdgcn_exp2f(b1 - rr1));
;         }
;         const bf16x8 sb = *(const LAS bf16x8*)(ST + (16 * vt + fr) * 136 + kb);
;         oacc = MFMA16(__builtin_bit_cast(bf16x8, ai), sb, oacc);
; #pragma unroll
;         for (int jj = 0; jj < 2; ++jj) {
;           const int J = J0 + jj; if (J > mt) continue;
;           const int srow = 16 * J + fr;
;           const bf16x8 kv = *(const LAS bf16x8*)(Kr + srow * 136 + kb);
;           const f32x4 c0 = *(const LAS f32x4*)(BC + srow * 132 + kb), c1 = *(const LAS f32x4*)(BC + srow * 132 + kb + 4);
;           u32x4 bk;
; #pragma unroll
;           for (int j = 0; j < 4; ++j) {
;             const float k0 = bf2f((bf16_t)kv[2 * j]), k1 = bf2f((bf16_t)kv[2 * j + 1]);
;             const float b0 = j < 2 ? c0[2 * j] : c1[2 * j - 4], b1 = j < 2 ? c0[2 * j + 1] : c1[2 * j - 3];
;             const float rr0 = j < 2 ? r0[2 * j] : r1[2 * j - 4], rr1 = j < 2 ? r0[2 * j + 1] : r1[2 * j - 3];
;             bk[j] = pk2(k0 * __builtin_amdgcn_exp2f(fminf(rr0 - b0, 115.f)), k1 * __builtin_amdgcn_exp2f(fminf(rr1 - b1, 115.f)));
;           }
;           if (jj == 0) a0 = MFMA16(__builtin_bit_cast(bf16x8, aq), __builtin_bit_cast(bf16x8, bk), a0);
;           else a1 = MFMA16(__builtin_bit_cast(bf16x8, aq), __builtin_bit_cast(bf16x8, bk), a1);
.LBB0_458:
	s_or_b64 exec, exec, vcc
	s_waitcnt lgkmcnt(0)
	s_nop 0
	v_mfma_f32_16x16x32_bf16 v[48:51], v[244:247], v[72:75], v[48:51]
	ds_read_b128 v[220:223], v249 offset:256
	ds_read_b128 v[224:227], v249 offset:272
	ds_read_b128 v[64:67], v91 offset:128
	ds_read_b128 v[56:59], v127 offset:35072
	ds_read_b128 v[52:55], v127 offset:35088
	ds_read_b128 v[68:71], v128 offset:35072
	ds_read_b128 v[60:63], v128 offset:35088
	s_waitcnt lgkmcnt(4)
	v_and_b32_e32 v117, 0xffff0000, v64
	v_lshlrev_b32_e32 v116, 16, v64
	v_and_b32_e32 v115, 0xffff0000, v65
	s_waitcnt lgkmcnt(1)
	v_sub_f32_e32 v33, v56, v68
	v_exp_f32_e32 v34, v33
	v_sub_f32_e32 v33, v57, v69
	v_exp_f32_e32 v35, v33
	v_sub_f32_e32 v33, v58, v70
	v_lshlrev_b32_e32 v114, 16, v65
	v_and_b32_e32 v113, 0xffff0000, v66
	v_pk_mul_f32 v[34:35], v[34:35], v[116:117]
	v_lshlrev_b32_e32 v112, 16, v66
	v_pk_mul_f32 v[230:231], v[34:35], v[220:221]
	v_cvt_pk_bf16_f32 v64, v34, v35
	v_cvt_pk_bf16_f32 v244, v230, v231
	v_exp_f32_e32 v34, v33
	v_sub_f32_e32 v33, v59, v71
	v_exp_f32_e32 v35, v33
	s_waitcnt lgkmcnt(0)
	v_sub_f32_e32 v33, v52, v60
	v_pk_mul_f32 v[34:35], v[34:35], v[114:115]
	s_nop 0
	v_pk_mul_f32 v[230:231], v[34:35], v[222:223]
	v_cvt_pk_bf16_f32 v65, v34, v35
	v_cvt_pk_bf16_f32 v245, v230, v231
	v_exp_f32_e32 v34, v33
	v_sub_f32_e32 v33, v53, v61
	v_exp_f32_e32 v35, v33
	v_sub_f32_e32 v33, v54, v62
	v_exp_f32_e32 v72, v33
	v_sub_f32_e32 v33, v55, v63
	v_exp_f32_e32 v73, v33
	v_pk_mul_f32 v[34:35], v[34:35], v[112:113]
	s_nop 0
	v_pk_mul_f32 v[230:231], v[34:35], v[224:225]
	v_cvt_pk_bf16_f32 v66, v34, v35
	v_cvt_pk_bf16_f32 v246, v230, v231
	v_and_b32_e32 v35, 0xffff0000, v67
	v_lshlrev_b32_e32 v34, 16, v67
	v_pk_mul_f32 v[72:73], v[72:73], v[34:35]
	s_nop 0
	v_pk_mul_f32 v[230:231], v[72:73], v[226:227]
	v_cvt_pk_bf16_f32 v67, v72, v73
	v_cvt_pk_bf16_f32 v247, v230, v231
	ds_read_b128 v[72:75], v129 offset:128
	s_and_saveexec_b64 vcc, s[24:25]
	s_cbranch_execz .LBB0_460
	ds_read_b128 v[148:151], v147 offset:35072
	ds_read_b128 v[152:155], v146 offset:17536
	ds_read_b128 v[156:159], v147 offset:35088
	s_waitcnt lgkmcnt(2)
	v_sub_f32_e32 v33, v68, v148
	v_min_f32_e32 v33, 0x42e60000, v33
	v_exp_f32_e32 v148, v33
	v_sub_f32_e32 v33, v70, v150
	v_min_f32_e32 v33, 0x42e60000, v33
	v_sub_f32_e32 v97, v69, v149
	v_exp_f32_e32 v150, v33
	v_sub_f32_e32 v33, v71, v151
	v_min_f32_e32 v97, 0x42e60000, v97
	v_min_f32_e32 v33, 0x42e60000, v33
	v_exp_f32_e32 v149, v97
	v_exp_f32_e32 v151, v33
	s_waitcnt lgkmcnt(0)
	v_sub_f32_e32 v33, v60, v156
	v_min_f32_e32 v33, 0x42e60000, v33
	v_and_b32_e32 v161, 0xffff0000, v152
	v_lshlrev_b32_e32 v160, 16, v152
	v_exp_f32_e32 v152, v33
	v_sub_f32_e32 v33, v61, v157
	v_min_f32_e32 v33, 0x42e60000, v33
	v_pk_mul_f32 v[148:149], v[148:149], v[160:161]
	v_and_b32_e32 v161, 0xffff0000, v153
	v_lshlrev_b32_e32 v160, 16, v153
	v_exp_f32_e32 v153, v33
	v_pk_mul_f32 v[150:151], v[150:151], v[160:161]
	v_sub_f32_e32 v33, v62, v158
	v_cvt_pk_bf16_f32 v148, v148, v149
	v_cvt_pk_bf16_f32 v149, v150, v151
	v_and_b32_e32 v151, 0xffff0000, v154
	v_lshlrev_b32_e32 v150, 16, v154
	v_min_f32_e32 v33, 0x42e60000, v33
	v_pk_mul_f32 v[150:151], v[152:153], v[150:151]
	v_exp_f32_e32 v152, v33
	v_sub_f32_e32 v33, v63, v159
	v_min_f32_e32 v33, 0x42e60000, v33
	v_exp_f32_e32 v153, v33
	v_and_b32_e32 v157, 0xffff0000, v155
	v_lshlrev_b32_e32 v156, 16, v155
	v_cvt_pk_bf16_f32 v150, v150, v151
	v_pk_mul_f32 v[152:153], v[152:153], v[156:157]
	s_nop 0
	v_cvt_pk_bf16_f32 v151, v152, v153
	s_nop 1
	v_mfma_f32_16x16x32_bf16 v[40:43], v[64:67], v[148:151], v[40:43]

; DI void hgrn_scan_phase(int wv, const P& p_, LAS unsigned char* lds, float* sumsq) {
;     ...
;       for (int ks = 0; ks < 4; ++ks) {
;         const int kb = 32 * ks + 8 * fq, trow = 16 * mt + fr;
;         const bf16x8 qv = *(const LAS bf16x8*)(Q + trow * 136 + kb);
;         const f32x4 bc0 = *(const LAS f32x4*)(BC + trow * 132 + kb), bc1 = *(const LAS f32x4*)(BC + trow * 132 + kb + 4);
;         const f32x4 r0 = *(const LAS f32x4*)(BC + (16 * mt) * 132 + kb), r1 = *(const LAS f32x4*)(BC + (16 * mt) * 132 + kb + 4);
;         u32x4 ai, aq;
; #pragma unroll
;         for (int j = 0; j < 4; ++j) {
;           const float q0 = bf2f((bf16_t)qv[2 * j]), q1 = bf2f((bf16_t)qv[2 * j + 1]);
;           const float b0 = j < 2 ? bc0[2 * j] : bc1[2 * j - 4], b1 = j < 2 ? bc0[2 * j + 1] : bc1[2 * j - 3];
;           const float rr0 = j < 2 ? r0[2 * j] : r1[2 * j - 4], rr1 = j < 2 ? r0[2 * j + 1] : r1[2 * j - 3];
;           ai[j] = pk2(q0 * __builtin_amdgcn_exp2f(b0), q1 * __builtin_amdgcn_exp2f(b1)); aq[j] = pk2(q0 * __builtin_amdgcn_exp2f(b0 - rr0), q1 * __builtin_amdgcn_exp2f(b1 - rr1));
;         }
;         const bf16x8 sb = *(const LAS bf16x8*)(ST + (16 * vt + fr) * 136 + kb);
;         oacc = MFMA16(__builtin_bit_cast(bf16x8, ai), sb, oacc);
; #pragma unroll
;         for (int jj = 0; jj < 2; ++jj) {
;           const int J = J0 + jj; if (J > mt) continue;
;           const int srow = 16 * J + fr;
;           const bf16x8 kv = *(const LAS bf16x8*)(Kr + srow * 136 + kb);
;           const f32x4 c0 = *(const LAS f32x4*)(BC + srow * 132 + kb), c1 = *(const LAS f32x4*)(BC + srow * 132 + kb + 4);
;           u32x4 bk;
; #pragma unroll
;           for (int j = 0; j < 4; ++j) {
;             const float k0 = bf2f((bf16_t)kv[2 * j]), k1 = bf2f((bf16_t)kv[2 * j + 1]);
;             const float b0 = j < 2 ? c0[2 * j] : c1[2 * j - 4], b1 = j < 2 ? c0[2 * j + 1] : c1[2 * j - 3];
;             const float rr0 = j < 2 ? r0[2 * j] : r1[2 * j - 4], rr1 = j < 2 ? r0[2 * j + 1] : r1[2 * j - 3];
;             bk[j] = pk2(k0 * __builtin_amdgcn_exp2f(fminf(rr0 - b0, 115.f)), k1 * __builtin_amdgcn_exp2f(fminf(rr1 - b1, 115.f)));
;           }
;           if (jj == 0) a0 = MFMA16(__builtin_bit_cast(bf16x8, aq), __builtin_bit_cast(bf16x8, bk), a0);
;           else a1 = MFMA16(__builtin_bit_cast(bf16x8, aq), __builtin_bit_cast(bf16x8, bk), a1);
.LBB0_462:
	s_or_b64 exec, exec, vcc
	s_waitcnt lgkmcnt(0)
	s_nop 0
	v_mfma_f32_16x16x32_bf16 v[48:51], v[244:247], v[72:75], v[48:51]
	ds_read_b128 v[220:223], v249 offset:384
	ds_read_b128 v[224:227], v249 offset:400
	ds_read_b128 v[64:67], v91 offset:192
	ds_read_b128 v[56:59], v127 offset:35200
	ds_read_b128 v[52:55], v127 offset:35216
	ds_read_b128 v[68:71], v128 offset:35200
	ds_read_b128 v[60:63], v128 offset:35216
	s_waitcnt lgkmcnt(4)
	v_and_b32_e32 v35, 0xffff0000, v64
	v_lshlrev_b32_e32 v34, 16, v64
	v_and_b32_e32 v113, 0xffff0000, v65
	s_waitcnt lgkmcnt(1)
	v_sub_f32_e32 v33, v56, v68
	v_exp_f32_e32 v72, v33
	v_sub_f32_e32 v33, v57, v69
	v_exp_f32_e32 v73, v33
	v_sub_f32_e32 v33, v58, v70
	v_lshlrev_b32_e32 v112, 16, v65
	v_and_b32_e32 v115, 0xffff0000, v66
	v_pk_mul_f32 v[72:73], v[72:73], v[34:35]
	v_lshlrev_b32_e32 v114, 16, v66
	v_pk_mul_f32 v[230:231], v[72:73], v[220:221]
	v_cvt_pk_bf16_f32 v64, v72, v73
	v_cvt_pk_bf16_f32 v244, v230, v231
	v_exp_f32_e32 v72, v33
	v_sub_f32_e32 v33, v59, v71
	v_exp_f32_e32 v73, v33
	s_waitcnt lgkmcnt(0)
	v_sub_f32_e32 v33, v52, v60
	v_and_b32_e32 v117, 0xffff0000, v67
	v_lshlrev_b32_e32 v116, 16, v67
	v_pk_mul_f32 v[72:73], v[72:73], v[112:113]
	s_nop 0
	v_pk_mul_f32 v[230:231], v[72:73], v[222:223]
	v_cvt_pk_bf16_f32 v65, v72, v73
	v_cvt_pk_bf16_f32 v245, v230, v231
	v_exp_f32_e32 v72, v33
	v_sub_f32_e32 v33, v53, v61
	v_exp_f32_e32 v73, v33
	v_sub_f32_e32 v33, v54, v62
	v_pk_mul_f32 v[72:73], v[72:73], v[114:115]
	s_nop 0
	v_pk_mul_f32 v[230:231], v[72:73], v[224:225]
	v_cvt_pk_bf16_f32 v66, v72, v73
	v_cvt_pk_bf16_f32 v246, v230, v231
	v_exp_f32_e32 v72, v33
	v_sub_f32_e32 v33, v55, v63
	v_exp_f32_e32 v73, v33
	s_nop 0
	v_pk_mul_f32 v[72:73], v[72:73], v[116:117]
	s_nop 0
	v_pk_mul_f32 v[230:231], v[72:73], v[226:227]
	v_cvt_pk_bf16_f32 v67, v72, v73
	v_cvt_pk_bf16_f32 v247, v230, v231
	ds_read_b128 v[72:75], v129 offset:192
	s_and_saveexec_b64 vcc, s[24:25]
	s_cbranch_execz .LBB0_464
	ds_read_b128 v[148:151], v147 offset:35200
	ds_read_b128 v[152:155], v146 offset:17600
	ds_read_b128 v[156:159], v147 offset:35216
	s_waitcnt lgkmcnt(2)
	v_sub_f32_e32 v33, v68, v148
	v_min_f32_e32 v33, 0x42e60000, v33
	v_exp_f32_e32 v148, v33
	v_sub_f32_e32 v33, v70, v150
	v_min_f32_e32 v33, 0x42e60000, v33
	v_sub_f32_e32 v97, v69, v149
	v_exp_f32_e32 v150, v33
	v_sub_f32_e32 v33, v71, v151
	v_min_f32_e32 v97, 0x42e60000, v97
	v_min_f32_e32 v33, 0x42e60000, v33
	v_exp_f32_e32 v149, v97
	v_exp_f32_e32 v151, v33
	s_waitcnt lgkmcnt(0)
	v_sub_f32_e32 v33, v60, v156
	v_min_f32_e32 v33, 0x42e60000, v33
	v_and_b32_e32 v161, 0xffff0000, v152
	v_lshlrev_b32_e32 v160, 16, v152
	v_exp_f32_e32 v152, v33
	v_sub_f32_e32 v33, v61, v157
	v_min_f32_e32 v33, 0x42e60000, v33
	v_pk_mul_f32 v[148:149], v[148:149], v[160:161]
	v_and_b32_e32 v161, 0xffff0000, v153
	v_lshlrev_b32_e32 v160, 16, v153
	v_exp_f32_e32 v153, v33
	v_pk_mul_f32 v[150:151], v[150:151], v[160:161]
	v_sub_f32_e32 v33, v62, v158
	v_cvt_pk_bf16_f32 v148, v148, v149
	v_cvt_pk_bf16_f32 v149, v150, v151
	v_and_b32_e32 v151, 0xffff0000, v154
	v_lshlrev_b32_e32 v150, 16, v154
	v_min_f32_e32 v33, 0x42e60000, v33
	v_pk_mul_f32 v[150:151], v[152:153], v[150:151]
	v_exp_f32_e32 v152, v33
	v_sub_f32_e32 v33, v63, v159
	v_min_f32_e32 v33, 0x42e60000, v33
	v_exp_f32_e32 v153, v33
	v_and_b32_e32 v157, 0xffff0000, v155
	v_lshlrev_b32_e32 v156, 16, v155
	v_cvt_pk_bf16_f32 v150, v150, v151
	v_pk_mul_f32 v[152:153], v[152:153], v[156:157]
	s_nop 0
	v_cvt_pk_bf16_f32 v151, v152, v153
	s_nop 1
	v_mfma_f32_16x16x32_bf16 v[40:43], v[64:67], v[148:151], v[40:43]

; #define LAS __attribute__((address_space(3)))
; DI void lds_barrier() { asm volatile("s_waitcnt lgkmcnt(0)\n\ts_barrier" ::: "memory"); }
; #define MFMA16(a, b, c) __builtin_amdgcn_mfma_f32_16x16x32_bf16((a), (b), (c), 0, 0, 0)
; DI void hgrn_scan_phase(int wv, const P& p_, LAS unsigned char* lds, float* sumsq) {
;     ...
; #pragma unroll
;       for (int jj = 0; jj < 2; ++jj) { const int J = J0 + jj;
; #pragma unroll
;         for (int reg = 0; reg < 4; ++reg) { const int tt = 16 * mt + 4 * fq + reg, ss = 16 * J + fr; const float v = jj == 0 ? a0[reg] : a1[reg];
;           AB[tt * 72 + ss] = (J <= mt && ss <= tt) ? f2bf(v) : (bf16_t)0; } }
;       lds_barrier();
; #pragma unroll
;       for (int k2 = 0; k2 < 2; ++k2) {
;         const bf16x8 af = *(const LAS bf16x8*)(AB + (16 * mt + fr) * 72 + 32 * k2 + 8 * fq);
;         const bf16x8 vb = *(const LAS bf16x8*)(VT + (16 * vt + fr) * 72 + 32 * k2 + 8 * fq);
;         oacc = MFMA16(af, vb, oacc);
;       }
; #pragma unroll
;       for (int reg = 0; reg < 4; ++reg) {
;         const int tok = b * SEQ + c * 64 + 16 * mt + 4 * fq + reg; const float v = oacc[reg];
;         oraw[(size_t)tok * 1024 + hh * 128 + vq * 32 + 16 * vt + fr] = f2bf(v);
;         float sq = v * v; sq += __shfl_xor(sq, 1); sq += __shfl_xor(sq, 2); sq += __shfl_xor(sq, 4); sq += __shfl_xor(sq, 8);
;         if (fr == 0) atomicAdd(sumsq + (size_t)tok * 8 + hh, sq);
;       }
.LBB0_466:
	s_or_b64 exec, exec, vcc
	v_cvt_pk_bf16_f32 v33, v40, s0
	v_cndmask_b32_e64 v33, v33, 0, s[4:5]
	ds_write_b16 v143, v33
	v_cvt_pk_bf16_f32 v33, v41, s0
	v_cndmask_b32_e64 v33, v33, 0, s[68:69]
	ds_write_b16 v143, v33 offset:144
	v_cvt_pk_bf16_f32 v33, v42, s0
	v_cndmask_b32_e64 v33, v33, 0, s[72:73]
	ds_write_b16 v143, v33 offset:288
	v_cvt_pk_bf16_f32 v33, v43, s0
	v_cndmask_b32_e64 v33, v33, 0, s[74:75]
	ds_write_b16 v143, v33 offset:432
	v_cvt_pk_bf16_f32 v33, v44, s0
	v_cndmask_b32_e64 v33, v33, 0, s[62:63]
	ds_write_b16 v130, v33
	v_cvt_pk_bf16_f32 v33, v45, s0
	v_cndmask_b32_e64 v33, v33, 0, s[82:83]
	ds_write_b16 v131, v33
	v_cvt_pk_bf16_f32 v33, v46, s0
	v_cndmask_b32_e64 v33, v33, 0, s[90:91]
	ds_write_b16 v132, v33
	v_cvt_pk_bf16_f32 v33, v47, s0
	v_cndmask_b32_e64 v33, v33, 0, s[0:1]
	ds_write_b16 v133, v33
	s_waitcnt lgkmcnt(0)
	s_barrier
	ds_read_b128 v[40:43], v123
	s_waitcnt lgkmcnt(9)
	v_mfma_f32_16x16x32_bf16 v[44:47], v[244:247], v[72:75], v[48:51]
	s_nop 2
	ds_read_b128 v[48:51], v123 offset:64
	ds_read_b128 v[52:55], v124
	ds_read_b128 v[56:59], v124 offset:64
	s_waitcnt lgkmcnt(1)
	v_mfma_f32_16x16x32_bf16 v[40:43], v[40:43], v[52:55], v[44:47]
	s_waitcnt lgkmcnt(0)
	v_mfma_f32_16x16x32_bf16 v[40:43], v[48:51], v[56:59], v[40:43]
	v_add_u32_e32 v34, -3, v102
	v_ashrrev_i32_e32 v35, 31, v34
	v_lshlrev_b64 v[48:49], 11, v[34:35]
	v_lshl_add_u64 v[48:49], v[108:109], 0, v[48:49]
	v_add_u32_e32 v50, -2, v102
	v_ashrrev_i32_e32 v51, 31, v50
	v_lshlrev_b64 v[52:53], 11, v[50:51]
	v_lshl_add_u64 v[52:53], v[108:109], 0, v[52:53]
	v_add_u32_e32 v54, -1, v102
	v_ashrrev_i32_e32 v55, 31, v54
	v_lshlrev_b64 v[56:57], 11, v[54:55]
	v_lshl_add_u64 v[56:57], v[108:109], 0, v[56:57]
	v_ashrrev_i32_e32 v103, 31, v102
	v_lshlrev_b64 v[58:59], 11, v[102:103]
	v_lshl_add_u64 v[58:59], v[108:109], 0, v[58:59]
	v_mul_f32_e32 v44, v40, v40
	v_mul_f32_e32 v45, v41, v41
	v_mul_f32_e32 v46, v42, v42
	v_mul_f32_e32 v47, v43, v43
	v_cvt_pk_bf16_f32 v33, v40, s0
	v_add_f32_dpp v44, v44, v44 quad_perm:[1,0,3,2] row_mask:0xf bank_mask:0xf
	v_add_f32_dpp v45, v45, v45 quad_perm:[1,0,3,2] row_mask:0xf bank_mask:0xf
	v_add_f32_dpp v46, v46, v46 quad_perm:[1,0,3,2] row_mask:0xf bank_mask:0xf
	v_add_f32_dpp v47, v47, v47 quad_perm:[1,0,3,2] row_mask:0xf bank_mask:0xf
	global_store_short v[48:49], v33, off
	v_add_f32_dpp v44, v44, v44 quad_perm:[2,3,0,1] row_mask:0xf bank_mask:0xf
	v_add_f32_dpp v45, v45, v45 quad_perm:[2,3,0,1] row_mask:0xf bank_mask:0xf
	v_add_f32_dpp v46, v46, v46 quad_perm:[2,3,0,1] row_mask:0xf bank_mask:0xf
	v_add_f32_dpp v47, v47, v47 quad_perm:[2,3,0,1] row_mask:0xf bank_mask:0xf
	v_cvt_pk_bf16_f32 v33, v41, s0
	v_add_f32_dpp v44, v44, v44 row_ror:4 row_mask:0xf bank_mask:0xf
	v_add_f32_dpp v45, v45, v45 row_ror:4 row_mask:0xf bank_mask:0xf
	v_add_f32_dpp v46, v46, v46 row_ror:4 row_mask:0xf bank_mask:0xf
	v_add_f32_dpp v47, v47, v47 row_ror:4 row_mask:0xf bank_mask:0xf
	global_store_short v[52:53], v33, off
	v_add_f32_dpp v44, v44, v44 row_ror:8 row_mask:0xf bank_mask:0xf
	v_add_f32_dpp v45, v45, v45 row_ror:8 row_mask:0xf bank_mask:0xf
	v_add_f32_dpp v46, v46, v46 row_ror:8 row_mask:0xf bank_mask:0xf
	v_add_f32_dpp v47, v47, v47 row_ror:8 row_mask:0xf bank_mask:0xf
	v_cvt_pk_bf16_f32 v33, v42, s0
	v_cvt_pk_bf16_f32 v40, v43, s0
	global_store_short v[56:57], v33, off
	global_store_short v[58:59], v40, off
	s_and_saveexec_b64 vcc, s[14:15]
	s_cbranch_execz .LBB0_441
	v_lshlrev_b64 v[34:35], 5, v[34:35]
	v_lshl_add_u64 v[34:35], s[60:61], 0, v[34:35]
	global_atomic_add_f32 v[34:35], v44, off
	v_lshlrev_b64 v[50:51], 5, v[50:51]
	v_lshl_add_u64 v[50:51], s[60:61], 0, v[50:51]
	global_atomic_add_f32 v[50:51], v45, off
	v_lshlrev_b64 v[54:55], 5, v[54:55]
	v_lshl_add_u64 v[54:55], s[60:61], 0, v[54:55]
	global_atomic_add_f32 v[54:55], v46, off
	v_lshlrev_b64 v[48:49], 5, v[102:103]
	v_lshl_add_u64 v[48:49], s[60:61], 0, v[48:49]
	global_atomic_add_f32 v[48:49], v47, off
	s_branch .LBB0_441
